# v02 + gla_job flat->global loads (waits unchanged)
# baseline (speedup 1.0000x reference)
.LBB0_677:
	s_and_b64 s[10:11], s[14:15], exec
	s_cselect_b32 s7, s18, s26
	s_lshl_b32 s36, s7, 5
	s_add_i32 s12, s36, 0x2000
	s_lshl_b32 s13, s26, 11
	s_and_b64 s[10:11], s[14:15], exec
	s_cselect_b32 s7, 32, 0x800
	s_cselect_b32 s71, s12, s13
	s_lshl_b32 s18, s16, 8
	s_waitcnt lgkmcnt(0)
	v_and_b32_e32 v136, 48, v158
	s_movk_i32 s20, 0x210
	v_lshlrev_b32_e32 v130, 3, v131
	s_ashr_i32 s19, s18, 31
	v_mad_u32_u24 v137, v161, s20, v136
	v_mad_u32_u24 v138, v161, s20, v130
	s_movk_i32 s20, 0xfe80
	s_lshl_b64 s[12:13], s[18:19], 1
	v_mad_i32_i24 v1, v161, s20, v137
	s_add_u32 s10, s28, s12
	v_add_u32_e32 v139, 0x8400, v137
	v_add_u32_e32 v135, 0x10800, v1
	v_add_u32_e32 v134, 0x1dc00, v1
	v_mov_b32_e32 v1, v158
	v_readlane_b32 s20, v252, 15
	s_addc_u32 s11, s34, s13
	v_readlane_b32 s21, v252, 16
	s_add_u32 s12, s35, s12
	v_ashrrev_i32_e32 v94, 5, v1
	v_lshlrev_b32_e32 v1, 3, v1
	s_mov_b32 s20, s21
	s_addc_u32 s13, s58, s13
	v_and_b32_e32 v1, 0xf8, v1
	s_lshl_b32 s24, s20, 6
	v_lshl_or_b32 v36, v94, 10, v1
	s_ashr_i32 s72, s71, 31
	s_ashr_i32 s21, s24, 31
	v_mov_b32_e32 v37, v34
	s_add_u32 s20, s24, s71
	v_lshlrev_b64 v[36:37], 1, v[36:37]
	s_addc_u32 s21, s21, s72
	s_sub_i32 s24, s7, s24
	v_lshl_add_u64 v[102:103], s[12:13], 0, v[36:37]
	v_lshl_add_u64 v[104:105], s[10:11], 0, v[36:37]
	v_mov_b32_e32 v36, v34
	v_mov_b32_e32 v37, v34
	s_min_i32 s37, s24, 64
	v_mov_b32_e32 v35, v34
	v_mov_b64_e32 v[72:73], v[36:37]
	v_mov_b64_e32 v[76:77], v[36:37]
	s_movk_i32 s84, 0x210
	v_cmp_gt_i32_e32 vcc, s37, v94
	v_mov_b64_e32 v[70:71], v[34:35]
	v_mov_b64_e32 v[74:75], v[34:35]
	s_and_saveexec_b64 s[24:25], vcc
	s_cbranch_execz .LBB0_679
	s_lshl_b64 s[42:43], s[20:21], 11
	v_lshl_add_u64 v[70:71], v[104:105], 0, s[42:43]
	v_lshl_add_u64 v[74:75], v[102:103], 0, s[42:43]
	global_load_dwordx4 v[70:73], v[70:71], off
	s_nop 0
	global_load_dwordx4 v[74:77], v[74:75], off
.LBB0_679:
	s_or_b64 exec, exec, s[24:25]
	v_add_u32_e32 v1, 16, v94
	v_mov_b64_e32 v[80:81], v[36:37]
	v_mov_b64_e32 v[84:85], v[36:37]
	v_cmp_gt_i32_e32 vcc, s37, v1
	v_mov_b64_e32 v[78:79], v[34:35]
	v_mov_b64_e32 v[82:83], v[34:35]
	s_and_saveexec_b64 s[24:25], vcc
	s_cbranch_execz .LBB0_681
	s_lshl_b64 s[42:43], s[20:21], 11
	s_bitset1_b32 s42, 15
	v_lshl_add_u64 v[36:37], v[104:105], 0, s[42:43]
	v_lshl_add_u64 v[82:83], v[102:103], 0, s[42:43]
	global_load_dwordx4 v[78:81], v[36:37], off
	s_nop 0
	global_load_dwordx4 v[82:85], v[82:83], off
.LBB0_681:
	s_or_b64 exec, exec, s[24:25]
	v_mov_b32_e32 v36, v34
	v_mov_b32_e32 v37, v34
	v_add_u32_e32 v1, 32, v94
	v_mov_b32_e32 v35, v34
	v_mov_b64_e32 v[88:89], v[36:37]
	v_mov_b64_e32 v[92:93], v[36:37]
	v_cmp_gt_i32_e32 vcc, s37, v1
	v_mov_b64_e32 v[86:87], v[34:35]
	v_mov_b64_e32 v[90:91], v[34:35]
	s_and_saveexec_b64 s[24:25], vcc
	s_cbranch_execz .LBB0_683
	s_lshl_b64 s[42:43], s[20:21], 11
	s_add_u32 s42, s42, 0x10000
	s_addc_u32 s43, s43, 0
	v_lshl_add_u64 v[36:37], v[104:105], 0, s[42:43]
	v_lshl_add_u64 v[90:91], v[102:103], 0, s[42:43]
	global_load_dwordx4 v[86:89], v[36:37], off
	s_nop 0
	global_load_dwordx4 v[90:93], v[90:91], off
.LBB0_683:
	s_or_b64 exec, exec, s[24:25]
	v_add_u32_e32 v1, 48, v94
	v_mov_b32_e32 v94, 0
	v_cmp_gt_i32_e32 vcc, s37, v1
	v_mov_b32_e32 v95, v94
	v_mov_b32_e32 v96, v94
	v_mov_b32_e32 v97, v94
	v_mov_b32_e32 v98, v94
	v_mov_b32_e32 v99, v94
	v_mov_b32_e32 v100, v94
	v_mov_b32_e32 v101, v94
	s_and_saveexec_b64 s[24:25], vcc
	s_cbranch_execz .LBB0_685
	s_lshl_b64 s[20:21], s[20:21], 11
	s_add_u32 s20, s20, 0x18000
	s_addc_u32 s21, s21, 0
	v_lshl_add_u64 v[36:37], v[104:105], 0, s[20:21]
	v_lshl_add_u64 v[98:99], v[102:103], 0, s[20:21]
	global_load_dwordx4 v[94:97], v[36:37], off
	s_nop 0
	global_load_dwordx4 v[98:101], v[98:99], off
.LBB0_685:
	s_or_b64 exec, exec, s[24:25]
	s_lshl_b32 s20, s16, 9
	s_ashr_i32 s21, s20, 31
	s_lshl_b64 s[16:17], s[16:17], 15
	s_add_u32 s73, s59, s16
	s_addc_u32 s74, s60, s17
	s_add_i32 s16, s26, 0x7c
	s_and_b64 s[14:15], s[14:15], exec
	s_cselect_b32 s75, s16, s36
	s_lshl_b64 s[16:17], s[20:21], 1
	v_readlane_b32 s20, v252, 15
	s_add_u32 s14, s65, s16
	v_readlane_b32 s21, v252, 16
	s_addc_u32 s15, s66, s17
	s_lshl_b32 s42, s27, 1
	v_mov_b32_e32 v1, v158
	s_mov_b32 s20, s21
	s_add_u32 s14, s14, s42
	s_addc_u32 s15, s15, 0
	s_lshl_b32 s26, s20, 6
	s_add_i32 s20, s20, s75
	s_ashr_i32 s21, s20, 31
	s_ashr_i32 s27, s26, 31
	s_sub_i32 s36, s7, s26
	s_lshl_b64 s[24:25], s[20:21], 17
	s_add_u32 s24, s73, s24
	v_lshlrev_b32_e32 v36, 3, v1
	s_addc_u32 s25, s74, s25
	v_mov_b32_e32 v37, v34
	v_lshl_add_u64 v[110:111], v[36:37], 1, s[24:25]
	s_movk_i32 s24, 0x2000
	v_add_co_u32_e32 v106, vcc, s24, v110
	s_movk_i32 s24, 0x4000
	s_nop 0
	v_addc_co_u32_e32 v107, vcc, 0, v111, vcc
	v_add_co_u32_e32 v112, vcc, s24, v110
	s_movk_i32 s24, 0x6000
	s_nop 0
	v_addc_co_u32_e32 v113, vcc, 0, v111, vcc
	v_add_co_u32_e32 v114, vcc, s24, v110
	global_load_dwordx4 v[102:105], v[110:111], off
	s_nop 0
	global_load_dwordx4 v[106:109], v[106:107], off
	v_addc_co_u32_e32 v115, vcc, 0, v111, vcc
	global_load_dwordx4 v[110:113], v[112:113], off
	s_nop 0
	global_load_dwordx4 v[114:117], v[114:115], off
	v_ashrrev_i32_e32 v124, 4, v1
	v_and_b32_e32 v1, 0x78, v36
	v_lshl_or_b32 v36, v124, 11, v1
	s_add_u32 s24, s26, s71
	v_lshl_add_u64 v[122:123], v[36:37], 1, s[14:15]
	v_mov_b32_e32 v36, v34
	s_addc_u32 s25, s27, s72
	s_min_i32 s36, s36, 64
	v_mov_b32_e32 v35, v34
	v_mov_b64_e32 v[120:121], v[36:37]
	v_cmp_gt_i32_e32 vcc, s36, v124
	v_mov_b64_e32 v[118:119], v[34:35]
	s_and_saveexec_b64 s[26:27], vcc
	s_cbranch_execz .LBB0_687
	s_lshl_b64 s[44:45], s[24:25], 12
	v_lshl_add_u64 v[118:119], v[122:123], 0, s[44:45]
	global_load_dwordx4 v[118:121], v[118:119], off
.LBB0_687:
	s_or_b64 exec, exec, s[26:27]
	v_add_u32_e32 v1, 32, v124
	v_mov_b64_e32 v[128:129], v[36:37]
	v_cmp_gt_i32_e32 vcc, s36, v1
	v_mov_b64_e32 v[126:127], v[34:35]
	s_and_saveexec_b64 s[26:27], vcc
	s_cbranch_execz .LBB0_689
	s_lshl_b64 s[24:25], s[24:25], 12
	v_lshl_add_u64 v[36:37], v[122:123], 0, s[24:25]
	v_add_co_u32_e32 v36, vcc, 0x20000, v36
	s_nop 1
	v_addc_co_u32_e32 v37, vcc, 0, v37, vcc
	global_load_dwordx4 v[126:129], v[36:37], off
.LBB0_689:
	s_or_b64 exec, exec, s[26:27]
	s_lshl_b64 s[18:19], s[18:19], 2
	s_add_u32 s24, s61, s18
	s_addc_u32 s26, s62, s19
	s_add_u32 s25, s63, s18
	s_movk_i32 s18, 0x80
	v_and_b32_e32 v140, 63, v158
	v_cmp_gt_i32_e64 s[36:37], s18, v158
	s_movk_i32 s18, 0x7f
	s_addc_u32 s27, s64, s19
	v_cmp_lt_i32_e32 vcc, s18, v158
	v_lshlrev_b32_e32 v132, 2, v140
	s_and_saveexec_b64 s[18:19], vcc
	s_xor_b64 s[18:19], exec, s[18:19]
	v_mov_b32_e32 v133, v34
	s_or_saveexec_b64 s[18:19], s[18:19]
	v_mov_b32_e32 v36, v34
	v_mov_b32_e32 v37, v34
	v_mov_b32_e32 v35, v34
	v_mov_b64_e32 v[124:125], v[36:37]
	v_mov_b64_e32 v[122:123], v[34:35]
	s_xor_b64 exec, exec, s[18:19]
	s_cbranch_execz .LBB0_693
	v_mov_b32_e32 v1, s27
	v_mov_b32_e32 v35, s26
	v_cmp_gt_i32_e32 vcc, 64, v158
	s_lshl_b64 s[20:21], s[20:21], 12
	v_lshlrev_b32_e32 v122, 4, v140
	v_cndmask_b32_e32 v37, v1, v35, vcc
	v_mov_b32_e32 v1, s25
	v_mov_b32_e32 v35, s24
	v_cndmask_b32_e32 v36, v1, v35, vcc
	v_lshl_add_u64 v[36:37], v[36:37], 0, s[20:21]
	v_mov_b32_e32 v123, v34
	v_lshl_add_u64 v[36:37], v[36:37], 0, v[122:123]
	global_load_dwordx4 v[122:125], v[36:37], off
	v_mov_b32_e32 v133, v34

.LBB0_695:
	v_mov_b32_e32 v1, v158
	s_movk_i32 s23, 0x90
	v_lshrrev_b32_e32 v35, 3, v1
	v_lshlrev_b32_e32 v36, 4, v1
	v_and_b32_e32 v37, 0x70, v36
	s_add_i32 s22, 0, 0x10800
	v_mul_lo_u32 v35, v35, s23
	v_add3_u32 v35, s22, v37, v35
	v_lshrrev_b32_e32 v1, 4, v1
	s_movk_i32 s22, 0x110
	s_waitcnt vmcnt(0)
	ds_write_b128 v35, v[102:105]
	ds_write_b128 v35, v[106:109] offset:9216
	ds_write_b128 v35, v[110:113] offset:18432
	ds_write_b128 v35, v[114:117] offset:27648
	v_and_b32_e32 v35, 0xf0, v36
	v_mul_lo_u32 v1, v1, s22
	v_readlane_b32 s22, v252, 6
	s_nop 1
	v_add3_u32 v1, s22, v35, v1
	ds_write_b128 v1, v[118:121]
	ds_write_b128 v1, v[126:129] offset:8704
	s_and_saveexec_b64 s[22:23], s[36:37]
	ds_write_b128 v210, v[122:125]
	s_or_b64 exec, exec, s[22:23]
	s_add_i32 s79, s79, 1
	s_cmp_lt_u32 s79, s76
	s_cselect_b64 s[22:23], -1, 0
	s_cmp_ge_u32 s79, s76
	s_waitcnt lgkmcnt(0)
	s_barrier
	s_cbranch_scc1 .LBB0_707
	v_mov_b32_e32 v1, v158
	s_mov_b32 s24, s79
	s_lshl_b32 s26, s24, 6
	v_ashrrev_i32_e32 v94, 5, v1
	v_lshlrev_b32_e32 v1, 3, v1
	s_ashr_i32 s25, s26, 31
	v_and_b32_e32 v1, 0xf8, v1
	s_add_u32 s24, s26, s71
	v_lshl_or_b32 v36, v94, 10, v1
	s_addc_u32 s25, s25, s72
	s_sub_i32 s26, s7, s26
	v_mov_b32_e32 v37, v34
	v_mov_b32_e32 v78, 0
	v_mov_b32_e32 v79, v34
	s_min_i32 s80, s26, 64
	v_lshlrev_b64 v[36:37], 1, v[36:37]
	v_mov_b32_e32 v80, v34
	v_mov_b32_e32 v81, v34
	v_mov_b64_e32 v[70:71], v[78:79]
	v_mov_b64_e32 v[74:75], v[78:79]
	v_lshl_add_u64 v[130:131], s[12:13], 0, v[36:37]
	v_lshl_add_u64 v[132:133], s[10:11], 0, v[36:37]
	v_cmp_gt_i32_e32 vcc, s80, v94
	v_mov_b64_e32 v[72:73], v[80:81]
	v_mov_b64_e32 v[76:77], v[80:81]
	s_and_saveexec_b64 s[26:27], vcc
	s_cbranch_execz .LBB0_700
	s_lshl_b64 s[82:83], s[24:25], 11
	v_lshl_add_u64 v[36:37], v[132:133], 0, s[82:83]
	v_lshl_add_u64 v[74:75], v[130:131], 0, s[82:83]
	global_load_dwordx4 v[70:73], v[36:37], off
	s_nop 0
	global_load_dwordx4 v[74:77], v[74:75], off
.LBB0_700:
	s_or_b64 exec, exec, s[26:27]
	v_add_u32_e32 v1, 16, v94
	v_mov_b64_e32 v[84:85], v[80:81]
	v_cmp_gt_i32_e32 vcc, s80, v1
	v_mov_b64_e32 v[82:83], v[78:79]
	s_and_saveexec_b64 s[26:27], vcc
	s_cbranch_execz .LBB0_702
	s_lshl_b64 s[82:83], s[24:25], 11
	s_bitset1_b32 s82, 15
	v_lshl_add_u64 v[36:37], v[132:133], 0, s[82:83]
	v_lshl_add_u64 v[82:83], v[130:131], 0, s[82:83]
	global_load_dwordx4 v[78:81], v[36:37], off
	s_nop 0
	global_load_dwordx4 v[82:85], v[82:83], off
.LBB0_702:
	s_or_b64 exec, exec, s[26:27]
	v_mov_b32_e32 v36, v34
	v_mov_b32_e32 v37, v34
	v_add_u32_e32 v1, 32, v94
	v_mov_b32_e32 v35, v34
	v_mov_b64_e32 v[88:89], v[36:37]
	v_mov_b64_e32 v[92:93], v[36:37]
	v_cmp_gt_i32_e32 vcc, s80, v1
	v_mov_b64_e32 v[86:87], v[34:35]
	v_mov_b64_e32 v[90:91], v[34:35]
	s_and_saveexec_b64 s[26:27], vcc
	s_cbranch_execz .LBB0_704
	s_lshl_b64 s[82:83], s[24:25], 11
	s_add_u32 s82, s82, 0x10000
	s_addc_u32 s83, s83, 0
	v_lshl_add_u64 v[36:37], v[132:133], 0, s[82:83]
	v_lshl_add_u64 v[90:91], v[130:131], 0, s[82:83]
	global_load_dwordx4 v[86:89], v[36:37], off
	s_nop 0
	global_load_dwordx4 v[90:93], v[90:91], off
.LBB0_704:
	s_or_b64 exec, exec, s[26:27]
	v_add_u32_e32 v1, 48, v94
	v_cmp_gt_i32_e32 vcc, s80, v1
	v_mov_b32_e32 v101, 0
	v_mov_b32_e32 v100, 0
	v_mov_b32_e32 v99, 0
	v_mov_b32_e32 v98, 0
	v_mov_b32_e32 v97, 0
	v_mov_b32_e32 v96, 0
	v_mov_b32_e32 v95, 0
	v_mov_b32_e32 v94, 0
	s_and_saveexec_b64 s[26:27], vcc
	s_cbranch_execz .LBB0_706
	s_lshl_b64 s[24:25], s[24:25], 11
	s_add_u32 s24, s24, 0x18000
	s_addc_u32 s25, s25, 0
	v_lshl_add_u64 v[36:37], v[132:133], 0, s[24:25]
	v_lshl_add_u64 v[98:99], v[130:131], 0, s[24:25]
	global_load_dwordx4 v[94:97], v[36:37], off
	s_nop 0
	global_load_dwordx4 v[98:101], v[98:99], off

.LBB0_711:
	s_nop 7
	v_cndmask_b32_e64 v1, v138, 0, s[48:49]
	v_cndmask_b32_e64 v35, v139, 0, s[50:51]
	v_cndmask_b32_e64 v37, v140, 0, s[52:53]
	v_cndmask_b32_e64 v138, v141, 0, s[54:55]
	v_cvt_pk_bf16_f32 v36, v1, v35
	v_cvt_pk_bf16_f32 v37, v37, v138
	ds_write_b64 v213, v[36:37]
	ds_read_b128 v[138:141], v155
	ds_read_b128 v[142:145], v180
	v_add_u32_e32 v1, 0x2000, v157
	v_add_u32_e32 v35, 0x4000, v157
	v_add_u32_e32 v246, 0x6000, v157
	s_waitcnt lgkmcnt(0)
	v_pk_mul_f32 v[36:37], v[4:5], v[140:141]
	v_pk_mul_f32 v[138:139], v[2:3], v[138:139]
	v_pk_mul_f32 v[140:141], v[10:11], v[142:143]
	v_cvt_pk_bf16_f32 v138, v138, v139
	v_cvt_pk_bf16_f32 v139, v36, v37
	v_pk_mul_f32 v[36:37], v[12:13], v[144:145]
	v_cvt_pk_bf16_f32 v140, v140, v141
	v_cvt_pk_bf16_f32 v141, v36, v37
	ds_read2_b64 v[142:145], v157 offset1:4
	ds_read2_b64 v[146:149], v1 offset0:32 offset1:36
	ds_read2_b64 v[150:153], v35 offset0:64 offset1:68
	ds_read2_b64 v[234:237], v246 offset0:96 offset1:100
	s_waitcnt lgkmcnt(0)
	v_mfma_f32_16x16x32_bf16 v[142:145], v[138:141], v[142:145], 0
	s_andn2_b64 vcc, exec, s[22:23]
	v_mfma_f32_16x16x32_bf16 v[146:149], v[138:141], v[146:149], 0
	v_mfma_f32_16x16x32_bf16 v[150:153], v[138:141], v[150:153], 0
	v_mfma_f32_16x16x32_bf16 v[138:141], v[138:141], v[234:237], 0
	ds_read_b128 v[234:237], v181
	ds_read_b128 v[238:241], v182
	s_waitcnt lgkmcnt(0)
	v_pk_mul_f32 v[36:37], v[8:9], v[236:237]
	v_pk_mul_f32 v[234:235], v[6:7], v[234:235]
	v_pk_mul_f32 v[236:237], v[14:15], v[238:239]
	v_cvt_pk_bf16_f32 v234, v234, v235
	v_cvt_pk_bf16_f32 v235, v36, v37
	v_pk_mul_f32 v[36:37], v[16:17], v[240:241]
	v_cvt_pk_bf16_f32 v236, v236, v237
	v_cvt_pk_bf16_f32 v237, v36, v37
	ds_read2_b64 v[238:241], v157 offset0:8 offset1:12
	s_waitcnt lgkmcnt(0)
	v_mfma_f32_16x16x32_bf16 v[142:145], v[234:237], v[238:241], v[142:145]
	ds_read2_b64 v[238:241], v1 offset0:40 offset1:44
	s_waitcnt lgkmcnt(0)
	v_mfma_f32_16x16x32_bf16 v[146:149], v[234:237], v[238:241], v[146:149]
	ds_read2_b64 v[238:241], v35 offset0:72 offset1:76
	s_waitcnt lgkmcnt(0)
	v_mfma_f32_16x16x32_bf16 v[150:153], v[234:237], v[238:241], v[150:153]
	ds_read2_b64 v[238:241], v246 offset0:104 offset1:108
	s_waitcnt lgkmcnt(0)
	v_mfma_f32_16x16x32_bf16 v[138:141], v[234:237], v[238:241], v[138:141]
	ds_read_b128 v[234:237], v183
	ds_read_b128 v[238:241], v184
	s_waitcnt lgkmcnt(0)
	v_pk_mul_f32 v[36:37], v[20:21], v[236:237]
	v_pk_mul_f32 v[234:235], v[18:19], v[234:235]
	v_pk_mul_f32 v[236:237], v[22:23], v[238:239]
	v_cvt_pk_bf16_f32 v234, v234, v235
	v_cvt_pk_bf16_f32 v235, v36, v37
	v_pk_mul_f32 v[36:37], v[24:25], v[240:241]
	v_cvt_pk_bf16_f32 v236, v236, v237
	v_cvt_pk_bf16_f32 v237, v36, v37
	ds_read2_b64 v[238:241], v157 offset0:16 offset1:20
	s_waitcnt lgkmcnt(0)
	v_mfma_f32_16x16x32_bf16 v[142:145], v[234:237], v[238:241], v[142:145]
	ds_read2_b64 v[238:241], v1 offset0:48 offset1:52
	s_waitcnt lgkmcnt(0)
	v_mfma_f32_16x16x32_bf16 v[146:149], v[234:237], v[238:241], v[146:149]
	ds_read2_b64 v[238:241], v35 offset0:80 offset1:84
	s_waitcnt lgkmcnt(0)
	v_mfma_f32_16x16x32_bf16 v[150:153], v[234:237], v[238:241], v[150:153]
	ds_read2_b64 v[238:241], v246 offset0:112 offset1:116
	s_waitcnt lgkmcnt(0)
	v_mfma_f32_16x16x32_bf16 v[138:141], v[234:237], v[238:241], v[138:141]
	ds_read_b128 v[234:237], v185
	ds_read_b128 v[238:241], v186
	s_waitcnt lgkmcnt(0)
	v_pk_mul_f32 v[36:37], v[28:29], v[236:237]
	v_pk_mul_f32 v[234:235], v[26:27], v[234:235]
	v_pk_mul_f32 v[236:237], v[30:31], v[238:239]
	v_cvt_pk_bf16_f32 v234, v234, v235
	v_cvt_pk_bf16_f32 v235, v36, v37
	v_pk_mul_f32 v[36:37], v[32:33], v[240:241]
	v_cvt_pk_bf16_f32 v236, v236, v237
	v_cvt_pk_bf16_f32 v237, v36, v37
	ds_read2_b64 v[238:241], v157 offset0:24 offset1:28
	s_waitcnt lgkmcnt(0)
	v_mfma_f32_16x16x32_bf16 v[142:145], v[234:237], v[238:241], v[142:145]
	ds_read2_b64 v[238:241], v1 offset0:56 offset1:60
	s_waitcnt lgkmcnt(0)
	v_mfma_f32_16x16x32_bf16 v[146:149], v[234:237], v[238:241], v[146:149]
	ds_read2_b64 v[238:241], v35 offset0:88 offset1:92
	s_waitcnt lgkmcnt(0)
	v_mfma_f32_16x16x32_bf16 v[150:153], v[234:237], v[238:241], v[150:153]
	ds_read2_b64 v[238:241], v246 offset0:120 offset1:124
	s_waitcnt lgkmcnt(0)
	v_mfma_f32_16x16x32_bf16 v[138:141], v[234:237], v[238:241], v[138:141]
	ds_read_b128 v[234:237], v187
	ds_read_b128 v[238:241], v188
	s_waitcnt lgkmcnt(0)
	v_pk_mul_f32 v[36:37], v[40:41], v[236:237]
	v_pk_mul_f32 v[234:235], v[38:39], v[234:235]
	v_pk_mul_f32 v[236:237], v[42:43], v[238:239]
	v_cvt_pk_bf16_f32 v234, v234, v235
	v_cvt_pk_bf16_f32 v235, v36, v37
	v_pk_mul_f32 v[36:37], v[44:45], v[240:241]
	v_cvt_pk_bf16_f32 v236, v236, v237
	v_cvt_pk_bf16_f32 v237, v36, v37
	ds_read2_b64 v[238:241], v157 offset0:32 offset1:36
	s_waitcnt lgkmcnt(0)
	v_mfma_f32_16x16x32_bf16 v[142:145], v[234:237], v[238:241], v[142:145]
	ds_read2_b64 v[238:241], v1 offset0:64 offset1:68
	s_waitcnt lgkmcnt(0)
	v_mfma_f32_16x16x32_bf16 v[146:149], v[234:237], v[238:241], v[146:149]
	ds_read2_b64 v[238:241], v35 offset0:96 offset1:100
	s_waitcnt lgkmcnt(0)
	v_mfma_f32_16x16x32_bf16 v[150:153], v[234:237], v[238:241], v[150:153]
	ds_read2_b64 v[238:241], v246 offset0:128 offset1:132
	s_waitcnt lgkmcnt(0)
	v_mfma_f32_16x16x32_bf16 v[138:141], v[234:237], v[238:241], v[138:141]
	ds_read_b128 v[234:237], v189
	ds_read_b128 v[238:241], v190
	s_waitcnt lgkmcnt(0)
	v_pk_mul_f32 v[36:37], v[48:49], v[236:237]
	v_pk_mul_f32 v[234:235], v[46:47], v[234:235]
	v_pk_mul_f32 v[236:237], v[50:51], v[238:239]
	v_cvt_pk_bf16_f32 v234, v234, v235
	v_cvt_pk_bf16_f32 v235, v36, v37
	v_pk_mul_f32 v[36:37], v[52:53], v[240:241]
	v_cvt_pk_bf16_f32 v236, v236, v237
	v_cvt_pk_bf16_f32 v237, v36, v37
	ds_read2_b64 v[238:241], v157 offset0:40 offset1:44
	s_waitcnt lgkmcnt(0)
	v_mfma_f32_16x16x32_bf16 v[142:145], v[234:237], v[238:241], v[142:145]
	ds_read2_b64 v[238:241], v1 offset0:72 offset1:76
	s_waitcnt lgkmcnt(0)
	v_mfma_f32_16x16x32_bf16 v[146:149], v[234:237], v[238:241], v[146:149]
	ds_read2_b64 v[238:241], v35 offset0:104 offset1:108
	s_waitcnt lgkmcnt(0)
	v_mfma_f32_16x16x32_bf16 v[150:153], v[234:237], v[238:241], v[150:153]
	ds_read2_b64 v[238:241], v246 offset0:136 offset1:140
	s_waitcnt lgkmcnt(0)
	v_mfma_f32_16x16x32_bf16 v[138:141], v[234:237], v[238:241], v[138:141]
	ds_read_b128 v[234:237], v191
	ds_read_b128 v[238:241], v192
	s_waitcnt lgkmcnt(0)
	v_pk_mul_f32 v[36:37], v[56:57], v[236:237]
	v_pk_mul_f32 v[234:235], v[54:55], v[234:235]
	v_pk_mul_f32 v[236:237], v[58:59], v[238:239]
	v_cvt_pk_bf16_f32 v234, v234, v235
	v_cvt_pk_bf16_f32 v235, v36, v37
	v_pk_mul_f32 v[36:37], v[60:61], v[240:241]
	v_cvt_pk_bf16_f32 v236, v236, v237
	v_cvt_pk_bf16_f32 v237, v36, v37
	ds_read2_b64 v[238:241], v157 offset0:48 offset1:52
	s_waitcnt lgkmcnt(0)
	v_mfma_f32_16x16x32_bf16 v[142:145], v[234:237], v[238:241], v[142:145]
	ds_read2_b64 v[238:241], v1 offset0:80 offset1:84
	s_waitcnt lgkmcnt(0)
	v_mfma_f32_16x16x32_bf16 v[146:149], v[234:237], v[238:241], v[146:149]
	ds_read2_b64 v[238:241], v35 offset0:112 offset1:116
	s_waitcnt lgkmcnt(0)
	v_mfma_f32_16x16x32_bf16 v[238:241], v[234:237], v[238:241], v[150:153]
	s_nop 2
	ds_read2_b64 v[150:153], v246 offset0:144 offset1:148
	s_waitcnt lgkmcnt(0)
	v_mfma_f32_16x16x32_bf16 v[138:141], v[234:237], v[150:153], v[138:141]
	ds_read_b128 v[150:153], v193
	ds_read_b128 v[234:237], v194
	s_waitcnt lgkmcnt(0)
	v_pk_mul_f32 v[36:37], v[64:65], v[152:153]
	v_pk_mul_f32 v[150:151], v[62:63], v[150:151]
	v_cvt_pk_bf16_f32 v243, v36, v37
	v_cvt_pk_bf16_f32 v242, v150, v151
	v_pk_mul_f32 v[36:37], v[68:69], v[236:237]
	v_pk_mul_f32 v[150:151], v[66:67], v[234:235]
	v_cvt_pk_bf16_f32 v245, v36, v37
	v_cvt_pk_bf16_f32 v244, v150, v151
	ds_read2_b64 v[150:153], v157 offset0:56 offset1:60
	ds_read2_b64 v[234:237], v246 offset0:152 offset1:156
	s_waitcnt lgkmcnt(0)
	v_mfma_f32_16x16x32_bf16 v[150:153], v[242:245], v[150:153], v[142:145]
	s_nop 2
	ds_read2_b64 v[142:145], v1 offset0:88 offset1:92
	s_waitcnt lgkmcnt(0)
	v_mfma_f32_16x16x32_bf16 v[146:149], v[242:245], v[142:145], v[146:149]
	ds_read2_b64 v[142:145], v35 offset0:120 offset1:124
	s_waitcnt lgkmcnt(0)
	s_barrier
	v_mfma_f32_16x16x32_bf16 v[142:145], v[242:245], v[142:145], v[238:241]
	v_mfma_f32_16x16x32_bf16 v[138:141], v[242:245], v[234:237], v[138:141]
	s_cbranch_vccnz .LBB0_719
	v_mov_b32_e32 v1, v158
	s_mov_b32 s22, s79
	v_ashrrev_i32_e32 v35, 5, v1
	v_lshlrev_b32_e32 v1, 4, v1
	v_and_b32_e32 v1, 0x1f0, v1
	v_mul_lo_u32 v35, v35, s84
	v_add3_u32 v1, 0, v1, v35
	s_waitcnt vmcnt(0)
	ds_write_b128 v1, v[70:73]
	ds_write_b128 v1, v[74:77] offset:33792
	ds_write_b128 v1, v[78:81] offset:8448
	ds_write_b128 v1, v[82:85] offset:42240
	ds_write_b128 v1, v[86:89] offset:16896
	ds_write_b128 v1, v[90:93] offset:50688
	ds_write_b128 v1, v[94:97] offset:25344
	ds_write_b128 v1, v[98:101] offset:59136
	v_mov_b32_e32 v1, v158
	s_lshl_b32 s26, s22, 6
	s_add_i32 s22, s22, s75
	s_ashr_i32 s23, s22, 31
	s_ashr_i32 s27, s26, 31
	s_sub_i32 s80, s7, s26
	s_lshl_b64 s[24:25], s[22:23], 17
	s_add_u32 s24, s73, s24
	v_lshlrev_b32_e32 v36, 3, v1
	s_addc_u32 s25, s74, s25
	v_mov_b32_e32 v37, v34
	v_lshl_add_u64 v[110:111], v[36:37], 1, s[24:25]
	s_movk_i32 s24, 0x2000
	v_add_co_u32_e32 v106, vcc, s24, v110
	s_movk_i32 s24, 0x4000
	s_nop 0
	v_addc_co_u32_e32 v107, vcc, 0, v111, vcc
	v_add_co_u32_e32 v112, vcc, s24, v110
	s_movk_i32 s24, 0x6000
	s_nop 0
	v_addc_co_u32_e32 v113, vcc, 0, v111, vcc
	v_add_co_u32_e32 v114, vcc, s24, v110
	global_load_dwordx4 v[102:105], v[110:111], off
	s_nop 0
	global_load_dwordx4 v[106:109], v[106:107], off
	v_addc_co_u32_e32 v115, vcc, 0, v111, vcc
	global_load_dwordx4 v[110:113], v[112:113], off
	s_nop 0
	global_load_dwordx4 v[114:117], v[114:115], off
	v_ashrrev_i32_e32 v35, 4, v1
	v_and_b32_e32 v1, 0x78, v36
	s_add_u32 s24, s26, s71
	v_mov_b32_e32 v126, 0
	v_mov_b32_e32 v127, v34
	v_lshl_or_b32 v36, v35, 11, v1
	s_addc_u32 s25, s27, s72
	s_min_i32 s80, s80, 64
	v_mov_b32_e32 v128, v34
	v_mov_b32_e32 v129, v34
	v_mov_b64_e32 v[118:119], v[126:127]
	v_lshl_add_u64 v[36:37], v[36:37], 1, s[14:15]
	v_cmp_gt_i32_e32 vcc, s80, v35
	v_mov_b64_e32 v[120:121], v[128:129]
	s_and_saveexec_b64 s[26:27], vcc
	s_cbranch_execz .LBB0_714
	s_lshl_b64 s[82:83], s[24:25], 12
	v_lshl_add_u64 v[118:119], v[36:37], 0, s[82:83]
	global_load_dwordx4 v[118:121], v[118:119], off
.LBB0_714:
	s_or_b64 exec, exec, s[26:27]
	v_add_u32_e32 v1, 32, v35
	v_cmp_gt_i32_e32 vcc, s80, v1
	s_and_saveexec_b64 s[26:27], vcc
	s_cbranch_execz .LBB0_716
	s_lshl_b64 s[24:25], s[24:25], 12
	v_lshl_add_u64 v[36:37], v[36:37], 0, s[24:25]
	v_add_co_u32_e32 v36, vcc, 0x20000, v36
	s_nop 1
	v_addc_co_u32_e32 v37, vcc, 0, v37, vcc
	global_load_dwordx4 v[126:129], v[36:37], off
.LBB0_716:
	s_or_b64 exec, exec, s[26:27]
	s_and_saveexec_b64 s[24:25], s[36:37]
	s_cbranch_execz .LBB0_718
	s_lshl_b64 s[22:23], s[22:23], 12
	v_lshl_add_u64 v[36:37], v[178:179], 0, s[22:23]
	global_load_dwordx4 v[122:125], v[36:37], off

.LBB0_719:
	ds_read_b128 v[234:237], v233
	s_add_u32 s22, s77, s71
	s_addc_u32 s23, 0, s72
	v_cmp_gt_i32_e32 vcc, s78, v161
	s_waitcnt lgkmcnt(0)
	v_mfma_f32_16x16x32_bf16 v[150:153], v[134:137], v[234:237], v[150:153]
	ds_read_b128 v[234:237], v233 offset:64
	s_waitcnt lgkmcnt(0)
	v_mfma_f32_16x16x32_bf16 v[150:153], v[130:133], v[234:237], v[150:153]
	s_and_saveexec_b64 s[24:25], vcc
	s_cbranch_execz .LBB0_721
	v_mov_b32_e32 v235, s23
	v_or_b32_e32 v234, s22, v161
	v_lshlrev_b64 v[234:235], 13, v[234:235]
	s_nop 2
	v_cvt_pk_bf16_f32 v36, v150, v151
	v_cvt_pk_bf16_f32 v37, v152, v153
	v_lshl_add_u64 v[234:235], v[176:177], 0, v[234:235]
	global_store_dwordx2 v[234:235], v[36:37], off

.LBB0_723:
	s_or_b64 exec, exec, s[24:25]
	s_waitcnt lgkmcnt(0)
	ds_read_b128 v[150:153], v233 offset:2304
	s_min_i32 s26, s78, 64
	v_cmp_gt_i32_e32 vcc, s26, v162
	s_waitcnt lgkmcnt(0)
	v_mfma_f32_16x16x32_bf16 v[146:149], v[134:137], v[150:153], v[146:149]
	ds_read_b128 v[150:153], v233 offset:2368
	s_waitcnt lgkmcnt(0)
	v_mfma_f32_16x16x32_bf16 v[146:149], v[130:133], v[150:153], v[146:149]
	s_and_saveexec_b64 s[24:25], vcc
	s_cbranch_execz .LBB0_725
	v_mov_b32_e32 v153, s23
	v_or_b32_e32 v152, s22, v162
	v_lshlrev_b64 v[152:153], 13, v[152:153]
	s_nop 2
	v_cvt_pk_bf16_f32 v150, v146, v147
	v_cvt_pk_bf16_f32 v151, v148, v149
	v_lshl_add_u64 v[152:153], v[176:177], 0, v[152:153]
	global_store_dwordx2 v[152:153], v[150:151], off

.LBB0_727:
	s_or_b64 exec, exec, s[24:25]
	s_waitcnt lgkmcnt(0)
	ds_read_b128 v[146:149], v233 offset:4608
	v_cmp_gt_i32_e32 vcc, s26, v172
	s_waitcnt lgkmcnt(0)
	v_mfma_f32_16x16x32_bf16 v[142:145], v[134:137], v[146:149], v[142:145]
	ds_read_b128 v[146:149], v233 offset:4672
	s_waitcnt lgkmcnt(0)
	v_mfma_f32_16x16x32_bf16 v[142:145], v[130:133], v[146:149], v[142:145]
	s_and_saveexec_b64 s[24:25], vcc
	s_cbranch_execz .LBB0_729
	v_lshl_add_u64 v[148:149], s[22:23], 0, v[172:173]
	v_lshlrev_b64 v[148:149], 13, v[148:149]
	s_nop 3
	v_cvt_pk_bf16_f32 v146, v142, v143
	v_cvt_pk_bf16_f32 v147, v144, v145
	v_lshl_add_u64 v[148:149], v[176:177], 0, v[148:149]
	global_store_dwordx2 v[148:149], v[146:147], off

.LBB0_731:
	s_or_b64 exec, exec, s[24:25]
	s_waitcnt lgkmcnt(0)
	ds_read_b128 v[142:145], v233 offset:6912
	v_cmp_gt_i32_e32 vcc, s26, v174
	s_waitcnt lgkmcnt(0)
	v_mfma_f32_16x16x32_bf16 v[138:141], v[134:137], v[142:145], v[138:141]
	ds_read_b128 v[142:145], v233 offset:6976
	s_waitcnt lgkmcnt(0)
	v_mfma_f32_16x16x32_bf16 v[138:141], v[130:133], v[142:145], v[138:141]
	s_and_saveexec_b64 s[24:25], vcc
	s_cbranch_execz .LBB0_733
	v_lshl_add_u64 v[144:145], s[22:23], 0, v[174:175]
	v_lshlrev_b64 v[144:145], 13, v[144:145]
	s_nop 3
	v_cvt_pk_bf16_f32 v142, v138, v139
	v_cvt_pk_bf16_f32 v143, v140, v141
	v_lshl_add_u64 v[144:145], v[176:177], 0, v[144:145]
	global_store_dwordx2 v[144:145], v[142:143], off

.LBB0_735:
	s_or_b64 exec, exec, s[24:25]
	ds_read_b128 v[138:141], v163
	v_cmp_gt_i32_e32 vcc, s26, v158
	s_and_b64 s[26:27], s[56:57], vcc
	s_waitcnt lgkmcnt(0)
	v_pk_mul_f32 v[4:5], v[4:5], v[140:141]
	v_pk_mul_f32 v[2:3], v[2:3], v[138:139]
	ds_read_b128 v[138:141], v218
	s_waitcnt lgkmcnt(0)
	v_mfma_f32_16x16x32_bf16 v[2:5], v[138:141], v[134:137], v[2:5]
	ds_read_b128 v[138:141], v218 offset:64
	s_waitcnt lgkmcnt(0)
	v_mfma_f32_16x16x32_bf16 v[2:5], v[138:141], v[130:133], v[2:5]
	ds_read_b128 v[138:141], v195
	s_waitcnt lgkmcnt(0)
	v_pk_mul_f32 v[12:13], v[12:13], v[140:141]
	v_pk_mul_f32 v[10:11], v[10:11], v[138:139]
	ds_read_b128 v[138:141], v218 offset:2304
	s_waitcnt lgkmcnt(0)
	v_mfma_f32_16x16x32_bf16 v[10:13], v[138:141], v[134:137], v[10:13]
	ds_read_b128 v[138:141], v218 offset:2368
	s_waitcnt lgkmcnt(0)
	v_mfma_f32_16x16x32_bf16 v[10:13], v[138:141], v[130:133], v[10:13]
	ds_read_b128 v[138:141], v196
	s_waitcnt lgkmcnt(0)
	v_pk_mul_f32 v[8:9], v[8:9], v[140:141]
	v_pk_mul_f32 v[6:7], v[6:7], v[138:139]
	ds_read_b128 v[138:141], v218 offset:4608
	s_waitcnt lgkmcnt(0)
	v_mfma_f32_16x16x32_bf16 v[6:9], v[138:141], v[134:137], v[6:9]
	ds_read_b128 v[138:141], v218 offset:4672
	s_waitcnt lgkmcnt(0)
	v_mfma_f32_16x16x32_bf16 v[6:9], v[138:141], v[130:133], v[6:9]
	ds_read_b128 v[138:141], v197
	s_waitcnt lgkmcnt(0)
	v_pk_mul_f32 v[16:17], v[16:17], v[140:141]
	v_pk_mul_f32 v[14:15], v[14:15], v[138:139]
	ds_read_b128 v[138:141], v218 offset:6912
	s_waitcnt lgkmcnt(0)
	v_mfma_f32_16x16x32_bf16 v[14:17], v[138:141], v[134:137], v[14:17]
	ds_read_b128 v[138:141], v218 offset:6976
	s_waitcnt lgkmcnt(0)
	v_mfma_f32_16x16x32_bf16 v[14:17], v[138:141], v[130:133], v[14:17]
	ds_read_b128 v[138:141], v198
	s_waitcnt lgkmcnt(0)
	v_pk_mul_f32 v[20:21], v[20:21], v[140:141]
	v_pk_mul_f32 v[18:19], v[18:19], v[138:139]
	ds_read_b128 v[138:141], v218 offset:9216
	s_waitcnt lgkmcnt(0)
	v_mfma_f32_16x16x32_bf16 v[18:21], v[138:141], v[134:137], v[18:21]
	ds_read_b128 v[138:141], v218 offset:9280
	s_waitcnt lgkmcnt(0)
	v_mfma_f32_16x16x32_bf16 v[18:21], v[138:141], v[130:133], v[18:21]
	ds_read_b128 v[138:141], v199
	s_waitcnt lgkmcnt(0)
	v_pk_mul_f32 v[24:25], v[24:25], v[140:141]
	v_pk_mul_f32 v[22:23], v[22:23], v[138:139]
	ds_read_b128 v[138:141], v218 offset:11520
	s_waitcnt lgkmcnt(0)
	v_mfma_f32_16x16x32_bf16 v[22:25], v[138:141], v[134:137], v[22:25]
	ds_read_b128 v[138:141], v218 offset:11584
	s_waitcnt lgkmcnt(0)
	v_mfma_f32_16x16x32_bf16 v[22:25], v[138:141], v[130:133], v[22:25]
	ds_read_b128 v[138:141], v200
	s_waitcnt lgkmcnt(0)
	v_pk_mul_f32 v[28:29], v[28:29], v[140:141]
	v_pk_mul_f32 v[26:27], v[26:27], v[138:139]
	ds_read_b128 v[138:141], v218 offset:13824
	s_waitcnt lgkmcnt(0)
	v_mfma_f32_16x16x32_bf16 v[26:29], v[138:141], v[134:137], v[26:29]
	ds_read_b128 v[138:141], v218 offset:13888
	s_waitcnt lgkmcnt(0)
	v_mfma_f32_16x16x32_bf16 v[26:29], v[138:141], v[130:133], v[26:29]
	ds_read_b128 v[138:141], v201
	s_waitcnt lgkmcnt(0)
	v_pk_mul_f32 v[32:33], v[32:33], v[140:141]
	v_pk_mul_f32 v[30:31], v[30:31], v[138:139]
	ds_read_b128 v[138:141], v218 offset:16128
	s_waitcnt lgkmcnt(0)
	v_mfma_f32_16x16x32_bf16 v[30:33], v[138:141], v[134:137], v[30:33]
	ds_read_b128 v[138:141], v218 offset:16192
	s_waitcnt lgkmcnt(0)
	v_mfma_f32_16x16x32_bf16 v[30:33], v[138:141], v[130:133], v[30:33]
	ds_read_b128 v[138:141], v202
	s_waitcnt lgkmcnt(0)
	v_pk_mul_f32 v[40:41], v[40:41], v[140:141]
	v_pk_mul_f32 v[38:39], v[38:39], v[138:139]
	ds_read_b128 v[138:141], v218 offset:18432
	s_waitcnt lgkmcnt(0)
	v_mfma_f32_16x16x32_bf16 v[36:39], v[138:141], v[134:137], v[38:41]
	ds_read_b128 v[138:141], v218 offset:18496
	s_waitcnt lgkmcnt(0)
	v_mfma_f32_16x16x32_bf16 v[38:41], v[138:141], v[130:133], v[36:39]
	ds_read_b128 v[138:141], v203
	s_waitcnt lgkmcnt(0)
	v_pk_mul_f32 v[44:45], v[44:45], v[140:141]
	v_pk_mul_f32 v[42:43], v[42:43], v[138:139]
	ds_read_b128 v[138:141], v218 offset:20736
	s_waitcnt lgkmcnt(0)
	v_mfma_f32_16x16x32_bf16 v[42:45], v[138:141], v[134:137], v[42:45]
	ds_read_b128 v[138:141], v218 offset:20800
	s_waitcnt lgkmcnt(0)
	v_mfma_f32_16x16x32_bf16 v[42:45], v[138:141], v[130:133], v[42:45]
	ds_read_b128 v[138:141], v204
	s_waitcnt lgkmcnt(0)
	v_pk_mul_f32 v[48:49], v[48:49], v[140:141]
	v_pk_mul_f32 v[46:47], v[46:47], v[138:139]
	ds_read_b128 v[138:141], v218 offset:23040
	s_waitcnt lgkmcnt(0)
	v_mfma_f32_16x16x32_bf16 v[46:49], v[138:141], v[134:137], v[46:49]
	ds_read_b128 v[138:141], v218 offset:23104
	s_waitcnt lgkmcnt(0)
	v_mfma_f32_16x16x32_bf16 v[46:49], v[138:141], v[130:133], v[46:49]
	ds_read_b128 v[138:141], v205
	s_waitcnt lgkmcnt(0)
	v_pk_mul_f32 v[52:53], v[52:53], v[140:141]
	v_pk_mul_f32 v[50:51], v[50:51], v[138:139]
	ds_read_b128 v[138:141], v218 offset:25344
	s_waitcnt lgkmcnt(0)
	v_mfma_f32_16x16x32_bf16 v[50:53], v[138:141], v[134:137], v[50:53]
	ds_read_b128 v[138:141], v218 offset:25408
	s_waitcnt lgkmcnt(0)
	v_mfma_f32_16x16x32_bf16 v[50:53], v[138:141], v[130:133], v[50:53]
	ds_read_b128 v[138:141], v206
	s_waitcnt lgkmcnt(0)
	v_pk_mul_f32 v[56:57], v[56:57], v[140:141]
	v_pk_mul_f32 v[54:55], v[54:55], v[138:139]
	ds_read_b128 v[138:141], v218 offset:27648
	s_waitcnt lgkmcnt(0)
	v_mfma_f32_16x16x32_bf16 v[54:57], v[138:141], v[134:137], v[54:57]
	ds_read_b128 v[138:141], v218 offset:27712
	s_waitcnt lgkmcnt(0)
	v_mfma_f32_16x16x32_bf16 v[54:57], v[138:141], v[130:133], v[54:57]
	ds_read_b128 v[138:141], v207
	s_waitcnt lgkmcnt(0)
	v_pk_mul_f32 v[60:61], v[60:61], v[140:141]
	v_pk_mul_f32 v[58:59], v[58:59], v[138:139]
	ds_read_b128 v[138:141], v218 offset:29952
	s_waitcnt lgkmcnt(0)
	v_mfma_f32_16x16x32_bf16 v[58:61], v[138:141], v[134:137], v[58:61]
	ds_read_b128 v[138:141], v218 offset:30016
	s_waitcnt lgkmcnt(0)
	v_mfma_f32_16x16x32_bf16 v[58:61], v[138:141], v[130:133], v[58:61]
	ds_read_b128 v[138:141], v208
	s_waitcnt lgkmcnt(0)
	v_pk_mul_f32 v[64:65], v[64:65], v[140:141]
	v_pk_mul_f32 v[62:63], v[62:63], v[138:139]
	ds_read_b128 v[138:141], v218 offset:32256
	s_waitcnt lgkmcnt(0)
	v_mfma_f32_16x16x32_bf16 v[62:65], v[138:141], v[134:137], v[62:65]
	ds_read_b128 v[138:141], v218 offset:32320
	s_waitcnt lgkmcnt(0)
	v_mfma_f32_16x16x32_bf16 v[62:65], v[138:141], v[130:133], v[62:65]
	ds_read_b128 v[138:141], v209
	s_waitcnt lgkmcnt(0)
	v_pk_mul_f32 v[68:69], v[68:69], v[140:141]
	v_pk_mul_f32 v[66:67], v[66:67], v[138:139]
	ds_read_b128 v[138:141], v218 offset:34560
	s_waitcnt lgkmcnt(0)
	v_mfma_f32_16x16x32_bf16 v[66:69], v[138:141], v[134:137], v[66:69]
	ds_read_b128 v[134:137], v218 offset:34624
	s_waitcnt lgkmcnt(0)
	s_barrier
	v_mfma_f32_16x16x32_bf16 v[66:69], v[134:137], v[130:133], v[66:69]
	s_and_saveexec_b64 s[24:25], s[26:27]
	s_cbranch_execz .LBB0_694
	ds_read_b128 v[130:133], v220
	ds_read_b128 v[134:137], v220 offset:16
	s_waitcnt lgkmcnt(0)
	v_mov_b32_e32 v36, v130
	v_mov_b32_e32 v37, v134
	v_mov_b32_e32 v134, v131
	v_mov_b32_e32 v130, v132
	v_mov_b32_e32 v131, v136
	v_mov_b32_e32 v136, v133
	v_pk_add_f32 v[36:37], v[36:37], v[134:135]
	v_pk_add_f32 v[130:131], v[130:131], v[136:137]
	s_nop 0
	v_pk_add_f32 v[36:37], v[36:37], v[130:131]
	s_nop 0
	v_add_f32_e32 v1, v36, v37
	v_lshl_add_u64 v[36:37], s[22:23], 0, v[158:159]
	v_lshlrev_b64 v[36:37], 7, v[36:37]
	v_lshl_add_u64 v[36:37], s[16:17], 0, v[36:37]
	global_store_dword v[36:37], v1, off
	s_branch .LBB0_694
